# cross-attention prompt loop: K/V tiles two ahead through a 3-slot LDS ring (vmcnt(4) at top) instead of one ahead through 2 slots
# speedup vs baseline: 1.0075x; 1.0075x over previous
; #define LAS __attribute__((address_space(3)))
; DI void cross_unit(Ctx A_, LAS unsigned char* lds, int kvb, int hc, size_t row0, int nrows, int wave, int lane) {
;     const int r = lane & 31, hh = lane >> 5, rg = wave & 3, dvh = wave >> 2;
;     bf16* P = P_;
;     const bf16* Kg = MKV_ + (size_t)kvb * NMEM * 2048 + hc * 256; const bf16* Vg = Kg + 1024;
;     LAS float* wsf = (LAS float*)(lds + WSF_OFF) + wave * 128;
;     const bool act = rg * 32 < nrows;
;     load_tile(lds, Kg, Vg, 0, wave, lane);
;     bf16x8 qr[16];
;     { const bf16* Qg = P + (row0 + rg * 32 + r) * PLD + C_QC + hc * 256 + hh * 8;
; #pragma unroll
;       for (int d0 = 0; d0 < 16; ++d0) qr[d0] = *(const bf16x8*)(Qg + d0 * 16); }
;     asm volatile("" : "+v"(qr[0]), "+v"(qr[1]), "+v"(qr[2]), "+v"(qr[3]), "+v"(qr[4]), "+v"(qr[5]), "+v"(qr[6]), "+v"(qr[7]), "+v"(qr[8]), "+v"(qr[9]), "+v"(qr[10]), "+v"(qr[11]), "+v"(qr[12]), "+v"(qr[13]), "+v"(qr[14]), "+v"(qr[15]));
;     f32x16 o[4];
; #pragma unroll
;     for (int nb = 0; nb < 4; ++nb)
; #pragma unroll
;         for (int i = 0; i < 16; ++i) o[nb][i] = 0.f;
;     float m = -INFINITY, l = 0.f;
;     const int g16 = (lane >> 4) & 1, p4 = lane & 3, q4 = (lane & 15) >> 2;
; #pragma unroll 1
;     for (int t = 0; t < 8; ++t) {
;         asm volatile("s_waitcnt vmcnt(0) lgkmcnt(0)" ::: "memory"); __builtin_amdgcn_s_barrier(); asm volatile("" ::: "memory");
;         if (t + 1 < 8) load_tile(lds + ((t + 1) & 1) * BUF, Kg, Vg, (t + 1) * 32, wave, lane);
.LBB0_924:
	s_and_b64 vcc, exec, s[30:31]
	s_cbranch_vccz .LBB0_898
	s_ashr_i32 s4, s63, 7
	s_ashr_i32 s5, s4, 31
	s_lshl_b32 s2, s63, 7
	s_lshl_b64 s[30:31], s[4:5], 12
	s_and_b32 s2, s2, 0xf80
	s_or_b32 s30, s30, s2
	s_lshl_b64 s[34:35], s[4:5], 20
	s_add_u32 s4, s42, s34
	s_addc_u32 s5, s43, s35
	s_lshl_b32 s2, s63, 3
	s_and_b32 s64, s2, 0x300
	s_lshl_b32 s2, s64, 1
	s_add_u32 s4, s4, s2
	s_addc_u32 s5, s5, 0
	v_mov_b32_e32 v167, v3
	v_or_b32_e32 v168, s80, v158
	v_or_b32_e32 v170, s45, v158
	v_lshl_add_u64 v[4:5], s[4:5], 0, v[166:167]
	v_ashrrev_i32_e32 v169, 31, v168
	v_ashrrev_i32_e32 v171, 31, v170
	s_add_u32 s4, s4, s8
	v_lshl_add_u64 v[6:7], v[168:169], 1, v[4:5]
	s_mov_b32 s65, m0
	s_mov_b32 m0, s37
	s_nop 0
	global_load_lds_dwordx4 v[6:7], off
	s_mov_b32 m0, s65
	v_lshl_add_u64 v[4:5], v[170:171], 1, v[4:5]
	s_addc_u32 s5, s5, s9
	v_lshlrev_b32_e32 v2, 1, v176
	s_mov_b32 s65, m0
	s_mov_b32 m0, s39
	s_nop 0
	global_load_lds_dwordx4 v[4:5], off
	s_mov_b32 m0, s65
	v_lshl_add_u64 v[4:5], s[4:5], 0, v[2:3]
	v_mov_b32_e32 v149, v3
	v_lshl_add_u64 v[4:5], v[4:5], 0, v[148:149]
	v_lshl_add_u64 v[6:7], v[4:5], 0, s[14:15]
	s_mov_b32 s4, m0
	s_mov_b32 m0, s47
	s_nop 0
	global_load_lds_dwordx4 v[6:7], off
	s_mov_b32 m0, s4
	v_lshl_add_u64 v[4:5], v[4:5], 0, s[16:17]
	s_mov_b32 s4, m0
	s_mov_b32 m0, s48
	s_nop 0
	global_load_lds_dwordx4 v[4:5], off
	s_mov_b32 m0, s4
	s_or_b32 s4, s30, s44
	v_or_b32_e32 v2, s4, v164
	v_readlane_b32 s4, v255, 9
	v_readlane_b32 s5, v255, 10
	v_mov_b32_e32 v163, v3
	s_lshl_b32 s63, s63, 4
	v_mov_b64_e32 v[4:5], s[4:5]
	v_mad_u64_u32 v[4:5], s[4:5], v2, s59, v[4:5]
	v_mad_i32_i24 v5, s31, v165, v5
	v_lshl_add_u64 v[4:5], v[4:5], 0, s[2:3]
	v_lshl_add_u64 v[4:5], v[4:5], 0, v[162:163]
	v_lshl_add_u64 v[6:7], v[4:5], 0, s[18:19]
	v_add_co_u32_e32 v4, vcc, s46, v4
	v_lshl_or_b32 v18, v172, 10, s34
	s_nop 0
	v_addc_co_u32_e32 v5, vcc, 0, v5, vcc
	global_load_dwordx4 v[98:101], v[4:5], off offset:2048
	global_load_dwordx4 v[102:105], v[6:7], off offset:480
	global_load_dwordx4 v[106:109], v[6:7], off offset:448
	global_load_dwordx4 v[110:113], v[6:7], off offset:416
	global_load_dwordx4 v[114:117], v[6:7], off offset:384
	global_load_dwordx4 v[118:121], v[6:7], off offset:352
	global_load_dwordx4 v[122:125], v[6:7], off offset:320
	global_load_dwordx4 v[126:129], v[6:7], off offset:288
	global_load_dwordx4 v[130:133], v[6:7], off offset:256
	global_load_dwordx4 v[134:137], v[6:7], off offset:224
	global_load_dwordx4 v[138:141], v[6:7], off offset:192
	global_load_dwordx4 v[142:145], v[6:7], off offset:160
	global_load_dwordx4 v[146:149], v[6:7], off offset:128
	global_load_dwordx4 v[150:153], v[6:7], off offset:96
	global_load_dwordx4 v[154:157], v[6:7], off offset:64
	global_load_dwordx4 v[158:161], v[6:7], off offset:32
	s_and_b32 s63, s63, 0x600
	v_or3_b32 v66, v18, s63, v173
	s_add_u32 s63, s57, s63
	s_addc_u32 s65, s58, 0
	v_mov_b32_e32 v16, v3
	v_mov_b32_e32 v17, v3
	v_mov_b32_e32 v67, s35
	s_add_u32 s34, s63, s34
	v_mov_b32_e32 v4, v3
	v_mov_b32_e32 v5, v3
	v_mov_b32_e32 v6, v3
	v_mov_b32_e32 v7, v3
	v_mov_b32_e32 v8, v3
	v_mov_b32_e32 v9, v3
	v_mov_b32_e32 v10, v3
	v_mov_b32_e32 v11, v3
	v_mov_b32_e32 v12, v3
	v_mov_b32_e32 v13, v3
	v_mov_b32_e32 v14, v3
	v_mov_b32_e32 v15, v3
	v_mov_b32_e32 v2, v3
	v_mov_b64_e32 v[32:33], v[16:17]
	v_mov_b64_e32 v[48:49], v[16:17]
	v_mov_b64_e32 v[64:65], v[16:17]
	v_lshl_add_u64 v[172:173], s[12:13], 0, v[66:67]
	s_addc_u32 s35, s65, s35
	v_mov_b64_e32 v[80:81], v[16:17]
	s_mov_b32 s2, 0
	v_cmp_gt_u32_e64 s[4:5], 32, v175
	v_mov_b32_e32 v163, 0
	v_mov_b32_e32 v183, 0xff800000
	v_mov_b64_e32 v[30:31], v[14:15]
	v_mov_b64_e32 v[28:29], v[12:13]
	v_mov_b64_e32 v[26:27], v[10:11]
	v_mov_b64_e32 v[24:25], v[8:9]
	v_mov_b64_e32 v[22:23], v[6:7]
	v_mov_b64_e32 v[20:21], v[4:5]
	v_mov_b64_e32 v[18:19], v[2:3]
	v_mov_b64_e32 v[46:47], v[14:15]
	v_mov_b64_e32 v[44:45], v[12:13]
	v_mov_b64_e32 v[42:43], v[10:11]
	v_mov_b64_e32 v[40:41], v[8:9]
	v_mov_b64_e32 v[38:39], v[6:7]
	v_mov_b64_e32 v[36:37], v[4:5]
	v_mov_b64_e32 v[34:35], v[2:3]
	v_mov_b64_e32 v[62:63], v[14:15]
	v_mov_b64_e32 v[60:61], v[12:13]
	v_mov_b64_e32 v[58:59], v[10:11]
	v_mov_b64_e32 v[56:57], v[8:9]
	v_mov_b64_e32 v[54:55], v[6:7]
	v_mov_b64_e32 v[52:53], v[4:5]
	v_mov_b64_e32 v[50:51], v[2:3]
	v_lshl_add_u64 v[166:167], s[34:35], 0, v[166:167]
	v_mov_b64_e32 v[78:79], v[14:15]
	v_mov_b64_e32 v[76:77], v[12:13]
	v_mov_b64_e32 v[74:75], v[10:11]
	v_mov_b64_e32 v[72:73], v[8:9]
	v_mov_b64_e32 v[70:71], v[6:7]
	v_mov_b64_e32 v[68:69], v[4:5]
	v_mov_b64_e32 v[66:67], v[2:3]
	s_waitcnt vmcnt(0)
	s_mov_b32 s98, 0x8000
	s_mov_b32 s34, s98
	v_lshl_add_u64 v[4:5], v[168:169], 1, v[166:167]
	s_add_i32 s35, s34, s33
	s_mov_b32 s63, m0
	s_mov_b32 m0, s35
	s_nop 0
	global_load_lds_dwordx4 v[4:5], off
	s_mov_b32 m0, s63
	v_lshl_add_u64 v[4:5], v[170:171], 1, v[166:167]
	s_add_i32 s34, s34, s38
	s_mov_b32 s63, m0
	s_mov_b32 m0, s34
	s_nop 0
	global_load_lds_dwordx4 v[4:5], off
	s_mov_b32 m0, s63
	s_add_i32 s34, s35, 0x4000
	s_mov_b32 s63, m0
	s_mov_b32 m0, s34
	s_nop 0
	global_load_lds_dwordx4 v[172:173], off
	s_mov_b32 m0, s63
	v_lshl_add_u64 v[4:5], v[172:173], 0, s[20:21]
	s_add_i32 s34, s35, 0x4400
	s_mov_b32 s35, m0
	s_mov_b32 m0, s34
	s_nop 0
	global_load_lds_dwordx4 v[4:5], off
	s_mov_b32 m0, s35
	v_lshl_add_u64 v[166:167], v[166:167], 0, s[22:23]
	v_lshl_add_u64 v[172:173], v[172:173], 0, s[22:23]
	s_mov_b32 s98, 0x10000
	s_mov_b32 s99, 0
.LBB0_926:
	s_cmp_eq_u32 s2, 0x38000
	s_cbranch_scc1 .Lc3_w0
	s_waitcnt vmcnt(4) lgkmcnt(0)
	s_branch .Lc3_w1

; DI void cross_unit(Ctx A_, LAS unsigned char* lds, int kvb, int hc, size_t row0, int nrows, int wave, int lane) {
;     ...
;     for (int t = 0; t < 8; ++t) {
;         asm volatile("s_waitcnt vmcnt(0) lgkmcnt(0)" ::: "memory"); __builtin_amdgcn_s_barrier(); asm volatile("" ::: "memory");
;         if (t + 1 < 8) load_tile(lds + ((t + 1) & 1) * BUF, Kg, Vg, (t + 1) * 32, wave, lane);
.Lc3_w1:
	s_barrier
	s_cmp_eq_u32 s2, 0x38000
	s_cbranch_scc1 .Lcross_touch_s
	s_cmp_eq_u32 s2, 0x30000
	s_cbranch_scc1 .LBB0_928
	s_mov_b32 s34, s98
	v_lshl_add_u64 v[4:5], v[168:169], 1, v[166:167]
	s_add_i32 s35, s34, s33
	s_mov_b32 s63, m0
	s_mov_b32 m0, s35
	s_nop 0
	global_load_lds_dwordx4 v[4:5], off
	s_mov_b32 m0, s63
	v_lshl_add_u64 v[4:5], v[170:171], 1, v[166:167]
	s_add_i32 s34, s34, s38
	s_mov_b32 s63, m0
	s_mov_b32 m0, s34
	s_nop 0
	global_load_lds_dwordx4 v[4:5], off
	s_mov_b32 m0, s63
	s_add_i32 s34, s35, 0x4000
	s_mov_b32 s63, m0
	s_mov_b32 m0, s34
	s_nop 0
	global_load_lds_dwordx4 v[172:173], off
	s_mov_b32 m0, s63
	v_lshl_add_u64 v[4:5], v[172:173], 0, s[20:21]
	s_add_i32 s34, s35, 0x4400
	s_mov_b32 s35, m0
	s_mov_b32 m0, s34
	s_nop 0
	global_load_lds_dwordx4 v[4:5], off
	s_mov_b32 m0, s35
	s_add_i32 s98, s98, 0x8000
	s_cmp_eq_u32 s98, 0x18000
	s_cselect_b32 s98, 0, s98
	s_branch .LBB0_928

; #define LAS __attribute__((address_space(3)))
; DI float bf2f(unsigned short u) { return __uint_as_float((unsigned)u << 16); }
; DI unsigned f2bf(float f) { unsigned u = __float_as_uint(f); return (u + 0x7fffu + ((u >> 16) & 1u)) >> 16; }
; DI float fexp2(float x) { return __builtin_amdgcn_exp2f(x); }
; DI int crow(int i, int hh) { return (i & 3) + 8 * (i >> 2) + 4 * hh; }
; DI void cross_unit(Ctx A_, LAS unsigned char* lds, int kvb, int hc, size_t row0, int nrows, int wave, int lane) {
;     ...
;         if (act) {
;             const LAS unsigned char* buf = lds + (t & 1) * BUF;
;             const LAS unsigned char* kb = buf + hh * 512 + r * 16;
;             f32x16 p0;
; #pragma unroll
;             for (int i = 0; i < 16; ++i) p0[i] = 0.f;
; #pragma unroll
;             for (int d0 = 0; d0 < 16; ++d0) p0 = __builtin_amdgcn_mfma_f32_32x32x16_bf16(*(const LAS bf16x8*)(kb + d0 * 1024), qr[d0], p0, 0, 0, 0);
;             float tm = p0[0];
; #pragma unroll
;             for (int i = 1; i < 16; ++i) tm = fmaxf(tm, p0[i]);
;             tm = fmaxf(tm, __shfl_xor(tm, 32));
;             if (__any(tm > m + RESC_THR)) {
;                 const float mn = fmaxf(m, tm), f = fexp2(m - mn); m = mn; l *= f;
;                 if (hh == 0) wsf[r] = f;
;                 float fr[16];
; #pragma unroll
;                 for (int i = 0; i < 16; ++i) fr[i] = wsf[crow(i, hh)];
; #pragma unroll
;                 for (int nb = 0; nb < 4; ++nb)
; #pragma unroll
;                     for (int i = 0; i < 16; ++i) o[nb][i] *= fr[i];
;             }
;     ...
;             for (int i = 0; i < 16; ++i) {
;                 const int q = rg * 32 + crow(i, hh);
;                 if (q < nrows) { const size_t eo = (row0 + q) * PLD + hc * 256 + dvh * 128 + nb * 32 + r; Y_[(row0 + q) * YLD + C_YC + hc * 256 + dvh * 128 + nb * 32 + r] = (bf16)f2bf(o[nb][i] * rl[i] * bf2f(P[eo + C_ZC])); }
.LctC_s:
	v_readfirstlane_b32 s34, v0
	s_lshr_b32 s34, s34, 6
	s_and_b32 s63, s34, 3
	s_lshl_b32 s63, s63, 5
	s_add_i32 s98, s98, s63
	s_lshr_b32 s63, s34, 2
	s_lshl_b32 s63, s63, 8
	s_lshl_b32 s100, s100, 9
	s_add_i32 s100, s100, s63
	s_add_i32 s100, s100, 0x5000
	s_mul_hi_u32 s99, s98, 0x5800
	s_mul_i32 s98, s98, 0x5800
	v_readlane_b32 s63, v255, 9
	v_readlane_b32 s101, v255, 10
	v_and_b32_e32 v206, 63, v0
	v_lshrrev_b32_e32 v207, 4, v206
	s_add_u32 s98, s98, s63
	s_addc_u32 s99, s99, s101
	s_add_u32 s98, s98, s100
	s_addc_u32 s99, s99, 0
	v_mul_u32_u24_e32 v207, 0x5800, v207
	v_and_b32_e32 v206, 15, v206
	v_lshl_or_b32 v206, v206, 4, v207
	s_lshl_b32 s34, s34, 13
	s_add_i32 s34, s34, 0x10000
	s_mov_b32 s101, m0
	s_mov_b32 m0, s34
	s_nop 0
	global_load_lds_dwordx4 v206, s[98:99]
	s_add_u32 s98, s98, 0x16000
	s_addc_u32 s99, s99, 0
	s_add_i32 s34, s34, 0x400
	s_mov_b32 m0, s34
	s_nop 0
	global_load_lds_dwordx4 v206, s[98:99]
	s_add_u32 s98, s98, 0x16000
	s_addc_u32 s99, s99, 0
	s_add_i32 s34, s34, 0x400
	s_mov_b32 m0, s34
	s_nop 0
	global_load_lds_dwordx4 v206, s[98:99]
	s_add_u32 s98, s98, 0x16000
	s_addc_u32 s99, s99, 0
	s_add_i32 s34, s34, 0x400
	s_mov_b32 m0, s34
	s_nop 0
	global_load_lds_dwordx4 v206, s[98:99]
	s_add_u32 s98, s98, 0x16000
	s_addc_u32 s99, s99, 0
	s_add_i32 s34, s34, 0x400
	s_mov_b32 m0, s34
	s_nop 0
	global_load_lds_dwordx4 v206, s[98:99]
	s_add_u32 s98, s98, 0x16000
	s_addc_u32 s99, s99, 0
	s_add_i32 s34, s34, 0x400
	s_mov_b32 m0, s34
	s_nop 0
	global_load_lds_dwordx4 v206, s[98:99]
	s_add_u32 s98, s98, 0x16000
	s_addc_u32 s99, s99, 0
	s_add_i32 s34, s34, 0x400
	s_mov_b32 m0, s34
	s_nop 0
	global_load_lds_dwordx4 v206, s[98:99]
	s_add_u32 s98, s98, 0x16000
	s_addc_u32 s99, s99, 0
	s_add_i32 s34, s34, 0x400
	s_mov_b32 m0, s34
	s_nop 0
	global_load_lds_dwordx4 v206, s[98:99]
	s_mov_b32 m0, s101
	s_mov_b32 s99, 0x8000
.LBB0_928:
	s_mov_b32 s34, s99
	s_add_i32 s63, s34, 0
	v_add3_u32 v2, s63, v177, v178
	ds_read_b128 v[4:7], v2
	ds_read_b128 v[8:11], v2 offset:1024
	ds_read_b128 v[236:239], v2 offset:2048
	ds_read_b128 v[240:243], v2 offset:3072
	ds_read_b128 v[244:247], v2 offset:4096
	ds_read_b128 v[248:251], v2 offset:5120
	s_waitcnt lgkmcnt(5)
	v_mfma_f32_32x32x16_bf16 v[82:97], v[4:7], v[98:101], 0
	ds_read_b128 v[4:7], v2 offset:6144
	s_waitcnt lgkmcnt(5)
	v_mfma_f32_32x32x16_bf16 v[82:97], v[8:11], v[158:161], v[82:97]
	ds_read_b128 v[8:11], v2 offset:7168
	s_waitcnt lgkmcnt(5)
	v_mfma_f32_32x32x16_bf16 v[82:97], v[236:239], v[154:157], v[82:97]
	ds_read_b128 v[236:239], v2 offset:8192
	s_waitcnt lgkmcnt(5)
	v_mfma_f32_32x32x16_bf16 v[82:97], v[240:243], v[150:153], v[82:97]
	ds_read_b128 v[240:243], v2 offset:9216
	s_waitcnt lgkmcnt(5)
	v_mfma_f32_32x32x16_bf16 v[82:97], v[244:247], v[146:149], v[82:97]
	ds_read_b128 v[244:247], v2 offset:10240
	s_waitcnt lgkmcnt(5)
	v_mfma_f32_32x32x16_bf16 v[82:97], v[248:251], v[142:145], v[82:97]
	ds_read_b128 v[248:251], v2 offset:11264
	s_waitcnt lgkmcnt(5)
	v_mfma_f32_32x32x16_bf16 v[82:97], v[4:7], v[138:141], v[82:97]
	ds_read_b128 v[4:7], v2 offset:12288
	s_waitcnt lgkmcnt(5)
	v_mfma_f32_32x32x16_bf16 v[82:97], v[8:11], v[134:137], v[82:97]
	ds_read_b128 v[8:11], v2 offset:13312
	s_waitcnt lgkmcnt(5)
	v_mfma_f32_32x32x16_bf16 v[82:97], v[236:239], v[130:133], v[82:97]
	ds_read_b128 v[236:239], v2 offset:14336
	s_waitcnt lgkmcnt(5)
	v_mfma_f32_32x32x16_bf16 v[82:97], v[240:243], v[126:129], v[82:97]
	ds_read_b128 v[240:243], v2 offset:15360
	s_waitcnt lgkmcnt(5)
	v_mfma_f32_32x32x16_bf16 v[82:97], v[244:247], v[122:125], v[82:97]
	s_waitcnt lgkmcnt(4)
	v_mfma_f32_32x32x16_bf16 v[82:97], v[248:251], v[118:121], v[82:97]
	s_waitcnt lgkmcnt(3)
	v_mfma_f32_32x32x16_bf16 v[82:97], v[4:7], v[114:117], v[82:97]
	s_waitcnt lgkmcnt(2)
	v_mfma_f32_32x32x16_bf16 v[82:97], v[8:11], v[110:113], v[82:97]
	s_waitcnt lgkmcnt(1)
	v_mfma_f32_32x32x16_bf16 v[82:97], v[236:239], v[106:109], v[82:97]
	s_waitcnt lgkmcnt(0)
	v_mfma_f32_32x32x16_bf16 v[82:97], v[240:243], v[102:105], v[82:97]
	s_nop 11
	v_max_f32_e32 v2, v83, v83
	v_max_f32_e32 v4, v82, v82
	v_max_f32_e32 v2, v4, v2
	v_max3_f32 v2, v2, v84, v85
	v_max3_f32 v2, v2, v86, v87
	v_max3_f32 v2, v2, v88, v89
	v_max3_f32 v2, v2, v90, v91
	v_max3_f32 v2, v2, v92, v93
	v_max3_f32 v2, v2, v94, v95
	v_max3_f32 v2, v2, v96, v97
	ds_bpermute_b32 v4, v204, v2
	s_waitcnt lgkmcnt(0)
	v_max_f32_e32 v4, v4, v4
	v_max_f32_e32 v2, v2, v4
	v_add_f32_e32 v4, 0x41000000, v183
	v_cmp_gt_f32_e32 vcc, v2, v4
	s_cbranch_vccz .LBB0_932
	v_max_f32_e32 v2, v2, v2
	v_max_f32_e32 v4, v183, v183
	v_max_f32_e32 v2, v4, v2
	v_sub_f32_e32 v4, v183, v2
	v_exp_f32_e32 v4, v4
	s_and_saveexec_b64 s[34:35], s[4:5]
	ds_write_b32 v179, v4
	s_or_b64 exec, exec, s[34:35]
	v_add_u32_e32 v5, s40, v162
	ds_read_b128 v[6:9], v5 offset:96
	ds_read_b128 v[10:13], v5 offset:64
	ds_read_b128 v[14:17], v5 offset:32
	ds_read_b128 v[184:187], v5
	v_mul_f32_e32 v163, v163, v4
	s_waitcnt lgkmcnt(3)
	v_pk_mul_f32 v[30:31], v[30:31], v[6:7]
	s_waitcnt lgkmcnt(2)
	v_pk_mul_f32 v[26:27], v[26:27], v[10:11]
	s_waitcnt lgkmcnt(1)
	v_pk_mul_f32 v[22:23], v[22:23], v[14:15]
	v_pk_mul_f32 v[32:33], v[32:33], v[8:9]
	v_pk_mul_f32 v[28:29], v[28:29], v[12:13]
	v_pk_mul_f32 v[24:25], v[24:25], v[16:17]
	s_waitcnt lgkmcnt(0)
	v_pk_mul_f32 v[20:21], v[20:21], v[186:187]
	v_pk_mul_f32 v[18:19], v[18:19], v[184:185]
	v_pk_mul_f32 v[46:47], v[46:47], v[6:7]
	v_pk_mul_f32 v[42:43], v[42:43], v[10:11]
	v_pk_mul_f32 v[38:39], v[38:39], v[14:15]
	v_pk_mul_f32 v[48:49], v[48:49], v[8:9]
	v_pk_mul_f32 v[44:45], v[44:45], v[12:13]
	v_pk_mul_f32 v[40:41], v[40:41], v[16:17]
	v_pk_mul_f32 v[36:37], v[36:37], v[186:187]
	v_pk_mul_f32 v[34:35], v[34:35], v[184:185]
	v_pk_mul_f32 v[62:63], v[62:63], v[6:7]
	v_pk_mul_f32 v[58:59], v[58:59], v[10:11]
	v_pk_mul_f32 v[54:55], v[54:55], v[14:15]
	v_pk_mul_f32 v[64:65], v[64:65], v[8:9]
	v_pk_mul_f32 v[60:61], v[60:61], v[12:13]
	v_pk_mul_f32 v[56:57], v[56:57], v[16:17]
	v_pk_mul_f32 v[52:53], v[52:53], v[186:187]
	v_pk_mul_f32 v[50:51], v[50:51], v[184:185]
	v_pk_mul_f32 v[78:79], v[78:79], v[6:7]
	v_pk_mul_f32 v[74:75], v[74:75], v[10:11]
	v_pk_mul_f32 v[70:71], v[70:71], v[14:15]
	v_pk_mul_f32 v[80:81], v[80:81], v[8:9]
	v_pk_mul_f32 v[76:77], v[76:77], v[12:13]
	v_pk_mul_f32 v[72:73], v[72:73], v[16:17]
	v_pk_mul_f32 v[68:69], v[68:69], v[186:187]
	v_pk_mul_f32 v[66:67], v[66:67], v[184:185]
	s_branch .LBB0_933

; #define LAS __attribute__((address_space(3)))
; DI float fexp2(float x) { return __builtin_amdgcn_exp2f(x); }
; DI s16x4 vtr(const LAS unsigned char* p) { return __builtin_bit_cast(s16x4, __builtin_amdgcn_ds_read_tr16_b64_v4i16((LAS v4i16_t*)p)); }
; DI void cross_unit(Ctx A_, LAS unsigned char* lds, int kvb, int hc, size_t row0, int nrows, int wave, int lane) {
;     ...
;             float ls = 0.f;
; #pragma unroll
;             for (int i = 0; i < 16; ++i) { p0[i] = fexp2(p0[i] - m); ls += p0[i]; }
;             l += ls;
;             const bf16x8 pf0 = pack8(p0, 0), pf1 = pack8(p0, 8);
;             const LAS unsigned char* vp = buf + KT + dvh * 8192 + g16 * 32 + p4 * 8 + (4 * hh + q4) * 64;
; #pragma unroll
;             for (int ks = 0; ks < 2; ++ks)
; #pragma unroll
;                 for (int nb = 0; nb < 4; ++nb) {
;                     const s16x4 lo = vtr(vp + nb * 2048 + ks * 1024), hi = vtr(vp + nb * 2048 + ks * 1024 + 512);
;                     const bf16x8 vf = __builtin_shufflevector(lo, hi, 0, 1, 2, 3, 4, 5, 6, 7);
;                     o[nb] = __builtin_amdgcn_mfma_f32_32x32x16_bf16(ks == 0 ? pf0 : pf1, vf, o[nb], 0, 0, 0);
;                 }
.LBB0_933:
	v_sub_f32_e32 v4, v82, v2
	v_exp_f32_e32 v16, v4
	v_sub_f32_e32 v4, v83, v2
	v_exp_f32_e32 v17, v4
	v_sub_f32_e32 v4, v84, v2
	v_exp_f32_e32 v183, v4
	v_sub_f32_e32 v4, v85, v2
	v_exp_f32_e32 v184, v4
	v_sub_f32_e32 v4, v86, v2
	v_exp_f32_e32 v185, v4
	v_sub_f32_e32 v4, v87, v2
	v_exp_f32_e32 v186, v4
	v_sub_f32_e32 v4, v88, v2
	v_exp_f32_e32 v187, v4
	v_sub_f32_e32 v4, v89, v2
	v_exp_f32_e32 v188, v4
	v_sub_f32_e32 v4, v90, v2
	s_add_i32 s63, s63, s41
	v_exp_f32_e32 v189, v4
	v_sub_f32_e32 v4, v91, v2
	v_add3_u32 v8, s63, v180, v176
	v_exp_f32_e32 v190, v4
	v_sub_f32_e32 v4, v92, v2
	v_add3_u32 v91, v8, v181, v182
	v_exp_f32_e32 v191, v4
	v_cvt_pk_bf16_f32 v4, v16, v17
	v_cvt_pk_bf16_f32 v5, v183, v184
	v_cvt_pk_bf16_f32 v6, v185, v186
	v_cvt_pk_bf16_f32 v7, v187, v188
	ds_read_b64_tr_b16 v[8:9], v91 offset:16384
	ds_read_b64_tr_b16 v[10:11], v91 offset:16896
	v_sub_f32_e32 v12, v93, v2
	v_exp_f32_e32 v192, v12
	ds_read_b64_tr_b16 v[12:13], v91 offset:17408
	ds_read_b64_tr_b16 v[14:15], v91 offset:17920
	s_waitcnt lgkmcnt(2)
	v_mfma_f32_32x32x16_bf16 v[18:33], v[4:7], v[8:11], v[18:33]
	ds_read_b64_tr_b16 v[8:9], v91 offset:18432
	ds_read_b64_tr_b16 v[10:11], v91 offset:18944
	v_sub_f32_e32 v82, v94, v2
	v_exp_f32_e32 v193, v82
	ds_read_b64_tr_b16 v[82:83], v91 offset:19456
	ds_read_b64_tr_b16 v[84:85], v91 offset:19968
	v_sub_f32_e32 v86, v95, v2
	v_exp_f32_e32 v194, v86
	v_sub_f32_e32 v86, v96, v2
	s_waitcnt lgkmcnt(2)
	v_mfma_f32_32x32x16_bf16 v[34:49], v[4:7], v[8:11], v[34:49]
	ds_read_b64_tr_b16 v[8:9], v91 offset:20480
	ds_read_b64_tr_b16 v[10:11], v91 offset:20992
	v_exp_f32_e32 v195, v86
	ds_read_b64_tr_b16 v[86:87], v91 offset:21504
	ds_read_b64_tr_b16 v[88:89], v91 offset:22016
	v_sub_f32_e32 v90, v97, v2
	v_exp_f32_e32 v196, v90
	v_cvt_pk_bf16_f32 v90, v189, v190
	v_cvt_pk_bf16_f32 v92, v193, v194
	s_waitcnt lgkmcnt(2)
	v_mfma_f32_32x32x16_bf16 v[50:65], v[4:7], v[8:11], v[50:65]
	ds_read_b64_tr_b16 v[8:9], v91 offset:22528
	ds_read_b64_tr_b16 v[10:11], v91 offset:23040
	ds_read_b64_tr_b16 v[94:95], v91 offset:23552
	ds_read_b64_tr_b16 v[96:97], v91 offset:24064
	v_cvt_pk_bf16_f32 v91, v191, v192
	v_cvt_pk_bf16_f32 v93, v195, v196
	s_add_i32 s99, s99, 0x8000
	s_cmp_eq_u32 s99, 0x18000
	s_cselect_b32 s99, 0, s99
	s_add_i32 s2, s2, 0x8000
	v_lshl_add_u64 v[172:173], v[172:173], 0, s[22:23]
	s_cmp_eq_u32 s2, 0x40000
	s_waitcnt lgkmcnt(2)
	v_mfma_f32_32x32x16_bf16 v[66:81], v[4:7], v[8:11], v[66:81]
	v_add_f32_e32 v4, 0, v16
	v_add_f32_e32 v4, v17, v4
	v_add_f32_e32 v4, v183, v4
	v_add_f32_e32 v4, v184, v4
	v_add_f32_e32 v4, v185, v4
	v_add_f32_e32 v4, v186, v4
	v_add_f32_e32 v4, v187, v4
	v_add_f32_e32 v4, v188, v4
	v_add_f32_e32 v4, v189, v4
	v_mfma_f32_32x32x16_bf16 v[18:33], v[90:93], v[12:15], v[18:33]
	v_add_f32_e32 v4, v190, v4
	v_add_f32_e32 v4, v191, v4
	v_add_f32_e32 v4, v192, v4
	v_add_f32_e32 v4, v193, v4
	v_add_f32_e32 v4, v194, v4
	v_add_f32_e32 v4, v195, v4
	v_add_f32_e32 v4, v196, v4
	v_mfma_f32_32x32x16_bf16 v[34:49], v[90:93], v[82:85], v[34:49]
	v_add_f32_e32 v163, v163, v4
	v_lshl_add_u64 v[166:167], v[166:167], 0, s[22:23]
	v_mfma_f32_32x32x16_bf16 v[50:65], v[90:93], v[86:89], v[50:65]
	s_waitcnt lgkmcnt(0)
	v_mfma_f32_32x32x16_bf16 v[66:81], v[90:93], v[94:97], v[66:81]
	s_cbranch_scc1 .LBB0_935
	v_mov_b32_e32 v183, v2
	s_branch .LBB0_926
